# DA bias table built once per attention phase per workgroup instead of once per unit
# speedup vs baseline: 1.0261x; 1.0021x over previous
; __global__ void __launch_bounds__(512, 2) mk_fwd(Args a) {
;     ...
;         else if (sub == 4) {
;             const float* lp = a.in[7] + l * 256;
;             const float d1 = wave_sum(lp[lane] * lp[64 + lane], lane), d2 = wave_sum(lp[128 + lane] * lp[192 + lane], lane);
;             const float lam_init = 0.8f - 0.6f * expf(-0.3f * (float)l), lam = expf(d1) - expf(d2) + lam_init;
;             const bool xl = (G == 256);
.LBB0_92:
	s_andn2_b64 vcc, exec, s[0:1]
	s_cbranch_vccnz .LBB0_272
	v_readlane_b32 s0, v253, 51
	s_cmp_eq_u32 s0, 4
	s_cbranch_scc0 .LBB0_272
	s_mov_b32 s0, 0
	v_writelane_b32 v255, s0, 40
	v_readlane_b32 s40, v252, 46
	v_readlane_b32 s2, v253, 43
	v_readlane_b32 s44, v252, 50
	v_readlane_b32 s45, v252, 51
	s_lshl_b32 s16, s2, 8
	v_readlane_b32 s46, v252, 52
	v_readlane_b32 s47, v252, 53
	v_readlane_b32 s48, v252, 54
	v_readlane_b32 s49, v252, 55
	v_readlane_b32 s50, v252, 56
	v_readlane_b32 s51, v252, 57
	v_readlane_b32 s52, v252, 58
	v_readlane_b32 s53, v252, 59
	v_readlane_b32 s54, v252, 60
	v_readlane_b32 s55, v252, 61
	s_mov_b64 s[4:5], s[44:45]
	s_lshl_b64 s[0:1], s[16:17], 2
	s_mov_b64 s[14:15], s[54:55]
	s_add_u32 s0, s14, s0
	s_addc_u32 s1, s15, s1
	v_lshlrev_b32_e32 v0, 2, v180
	global_load_dword v2, v0, s[0:1]
	global_load_dword v3, v0, s[0:1] offset:256
	global_load_dword v4, v0, s[0:1] offset:512
	global_load_dword v5, v0, s[0:1] offset:768
	v_xor_b32_e32 v7, 4, v0
	v_xor_b32_e32 v8, 8, v0
	s_waitcnt lgkmcnt(0)
	v_cvt_f32_u32_e32 v6, s2
	v_readlane_b32 s1, v253, 42
	s_cmpk_lg_i32 s1, 0x100
	v_xor_b32_e32 v9, 16, v0
	s_cselect_b64 s[4:5], -1, 0
	v_writelane_b32 v254, s4, 20
	v_readlane_b32 s0, v251, 19
	v_mul_f32_e32 v6, 0xbe99999a, v6
	v_writelane_b32 v254, s5, 21
	s_add_i32 s0, s1, s0
	v_mul_f32_e32 v12, 0x3fb8aa3b, v6
	v_writelane_b32 v254, s0, 23
	s_lshl_b32 s16, s2, 6
	s_mov_b32 s0, 0x3fb8aa3b
	v_readlane_b32 s64, v253, 7
	s_mov_b64 s[6:7], s[46:47]
	v_fma_f32 v13, v6, s0, -v12
	s_lshl_b64 s[0:1], s[16:17], 2
	v_readlane_b32 s66, v253, 9
	v_readlane_b32 s67, v253, 10
	s_add_u32 s6, s66, s0
	v_xor_b32_e32 v10, 32, v0
	s_addc_u32 s7, s67, s1
	v_readlane_b32 s80, v253, 23
	v_writelane_b32 v254, s6, 24
	v_readlane_b32 s81, v253, 24
	s_add_u32 s0, s80, s0
	v_writelane_b32 v254, s7, 25
	s_addc_u32 s1, s81, s1
	s_mul_i32 s16, s2, 0x60
	v_writelane_b32 v254, s0, 26
	v_readlane_b32 s76, v253, 19
	v_readlane_b32 s77, v253, 20
	v_writelane_b32 v254, s1, 27
	s_lshl_b64 s[0:1], s[16:17], 2
	s_add_u32 s0, s76, s0
	v_xor_b32_e32 v11, 64, v0
	s_addc_u32 s1, s77, s1
	s_mov_b32 s4, 0xc2ce8ed0
	v_writelane_b32 v254, s0, 28
	s_mov_b32 s5, 0x42b17218
	v_cmp_ngt_f32_e32 vcc, s4, v6
	v_fmac_f32_e32 v13, 0x32a5705f, v6
	v_writelane_b32 v254, s1, 29
	v_cmp_nlt_f32_e64 s[0:1], s5, v6
	v_rndne_f32_e32 v14, v12
	v_sub_f32_e32 v12, v12, v14
	v_xor_b32_e32 v0, 0x80, v0
	v_add_f32_e32 v12, v12, v13
	v_cvt_i32_f32_e32 v14, v14
	v_readlane_b32 s3, v253, 44
	s_lshl_b32 s16, s2, 7
	s_lshl_b64 s[2:3], s[16:17], 2
	v_readlane_b32 s65, v253, 8
	s_add_u32 s2, s64, s2
	s_addc_u32 s3, s65, s3
	v_writelane_b32 v254, s2, 30
	s_mov_b64 s[8:9], s[48:49]
	s_mov_b64 s[10:11], s[50:51]
	v_writelane_b32 v254, s3, 31
	s_mov_b64 s[12:13], s[52:53]
	s_mov_b32 s52, 0x800000
	s_mov_b32 s6, 0
	v_readlane_b32 s41, v252, 47
	v_readlane_b32 s42, v252, 48
	v_readlane_b32 s43, v252, 49
	v_readlane_b32 s68, v253, 11
	v_readlane_b32 s69, v253, 12
	v_readlane_b32 s70, v253, 13
	v_readlane_b32 s71, v253, 14
	v_readlane_b32 s72, v253, 15
	v_readlane_b32 s73, v253, 16
	v_readlane_b32 s74, v253, 17
	v_readlane_b32 s75, v253, 18
	v_readlane_b32 s78, v253, 21
	s_waitcnt vmcnt(0)
	v_mul_f32_e32 v15, v2, v3
	ds_bpermute_b32 v15, v7, v15
	v_mul_f32_e32 v16, v4, v5
	ds_bpermute_b32 v7, v7, v16
	v_readlane_b32 s79, v253, 22
	v_readlane_b32 s82, v253, 25
	s_waitcnt lgkmcnt(0)
	v_fmac_f32_e32 v15, v2, v3
	ds_bpermute_b32 v2, v8, v15
	v_fmac_f32_e32 v7, v4, v5
	ds_bpermute_b32 v3, v8, v7
	v_exp_f32_e32 v4, v12
	v_readlane_b32 s83, v253, 26
	s_waitcnt lgkmcnt(1)
	v_add_f32_e32 v2, v15, v2
	ds_bpermute_b32 v5, v9, v2
	s_waitcnt lgkmcnt(1)
	v_add_f32_e32 v3, v7, v3
	ds_bpermute_b32 v7, v9, v3
	v_ldexp_f32 v4, v4, v14
	v_cndmask_b32_e32 v4, 0, v4, vcc
	s_waitcnt lgkmcnt(1)
	v_add_f32_e32 v2, v2, v5
	ds_bpermute_b32 v5, v10, v2
	s_waitcnt lgkmcnt(1)
	v_add_f32_e32 v3, v3, v7
	ds_bpermute_b32 v7, v10, v3
	v_mov_b32_e32 v10, 0x7f800000
	v_cndmask_b32_e64 v4, v10, v4, s[0:1]
	s_waitcnt lgkmcnt(1)
	v_add_f32_e32 v2, v2, v5
	ds_bpermute_b32 v5, v11, v2
	s_waitcnt lgkmcnt(1)
	v_add_f32_e32 v3, v3, v7
	ds_bpermute_b32 v6, v11, v3
	s_mov_b32 s0, 0x3fb8aa3b
	v_readlane_b32 s84, v253, 27
	s_waitcnt lgkmcnt(1)
	v_add_f32_e32 v2, v2, v5
	ds_bpermute_b32 v5, v0, v2
	s_waitcnt lgkmcnt(1)
	v_add_f32_e32 v3, v3, v6
	ds_bpermute_b32 v0, v0, v3
	v_mov_b32_e32 v6, 0x3f4ccccd
	v_fmamk_f32 v4, v4, 0xbf19999a, v6
	s_waitcnt lgkmcnt(1)
	v_add_f32_e32 v2, v2, v5
	v_cmp_ngt_f32_e32 vcc, s4, v2
	s_waitcnt lgkmcnt(0)
	v_add_f32_e32 v0, v3, v0
	v_mul_f32_e32 v3, 0x3fb8aa3b, v2
	v_mul_f32_e32 v5, 0x3fb8aa3b, v0
	v_fma_f32 v6, v2, s0, -v3
	v_rndne_f32_e32 v7, v3
	v_fma_f32 v8, v0, s0, -v5
	v_rndne_f32_e32 v9, v5
	v_fmac_f32_e32 v6, 0x32a5705f, v2
	v_sub_f32_e32 v3, v3, v7
	v_fmac_f32_e32 v8, 0x32a5705f, v0
	v_sub_f32_e32 v5, v5, v9
	v_add_f32_e32 v3, v3, v6
	v_cvt_i32_f32_e32 v7, v7
	v_exp_f32_e32 v3, v3
	v_add_f32_e32 v5, v5, v8
	v_cvt_i32_f32_e32 v6, v9
	v_exp_f32_e32 v5, v5
	v_ldexp_f32 v3, v3, v7
	v_cndmask_b32_e32 v3, 0, v3, vcc
	v_cmp_ngt_f32_e32 vcc, s4, v0
	v_ldexp_f32 v5, v5, v6
	v_readlane_b32 s0, v253, 40
	v_cndmask_b32_e32 v5, 0, v5, vcc
	v_cmp_nlt_f32_e32 vcc, s5, v2
	v_readlane_b32 s1, v253, 41
	s_add_u32 s2, s0, 0x24018000
	v_cndmask_b32_e32 v2, v10, v3, vcc
	v_cmp_nlt_f32_e32 vcc, s5, v0
	s_addc_u32 s3, s1, 0
	v_writelane_b32 v254, s2, 32
	v_cndmask_b32_e32 v0, v10, v5, vcc
	s_add_u32 s0, s0, 0x27000100
	v_writelane_b32 v254, s3, 33
	s_addc_u32 s1, s1, 0
	v_sub_f32_e32 v0, v2, v0
	v_writelane_b32 v254, s0, 34
	v_add_f32_e32 v148, v4, v0
	v_sub_f32_e32 v181, 1.0, v4
	v_writelane_b32 v254, s1, 35
	v_mov_b32_e32 v149, v148
	v_readlane_b32 s85, v253, 28
	v_readlane_b32 s86, v253, 29
	v_readlane_b32 s87, v253, 30
	v_readlane_b32 s88, v253, 31
	v_readlane_b32 s89, v253, 32
	v_readlane_b32 s90, v253, 33
	v_readlane_b32 s91, v253, 34
	v_readlane_b32 s92, v253, 35
	v_readlane_b32 s93, v253, 36
	v_readlane_b32 s94, v253, 37
	v_readlane_b32 s95, v253, 38
	s_branch .LBB0_98

; #define LAS __attribute__((address_space(3)))
; template <int MODE>
; DI void attn_unit(LAS unsigned char* lds, const bf16_t* Qg, int ldq, const bf16_t* Kg, int ldk, const bf16_t* VTg, int ldvt, bf16_t* Og, int ldo,
;                   int q0, int NT, const float* gout, const float* relb, float lam, float osc, const float* qgain) {
;     ...
;     if (MODE == 0) {
;         LAS float* tb = (LAS float*)(lds + TBL);
;         for (int idx = tid; idx < 640; idx += 512) { const int m2 = idx / 320, rel = (idx % 320) - 256; const int n = rel < 0 ? -rel : rel;
;             int bk = rel > 0 ? 16 : 0; if (n < 8) bk += n; else { int lg = (31 - __clz(n * n)) + 2; bk += lg > 15 ? 15 : lg; }
;             tb[idx] = (relb[bk * 8 + m2] - relb[15 * 8 + m2]) * LOG2E; }
;         c15 = relb[15 * 8 + mm] * LOG2E;
.LBB0_142:
	s_and_b64 vcc, exec, s[0:1]
	s_cbranch_vccz .LBB0_96
	s_cmp_lg_u32 s3, 0
	s_cbranch_scc0 .LBB0_172
	s_lshl_b64 s[8:9], s[16:17], 23
	v_readlane_b32 s0, v254, 2
	v_readlane_b32 s1, v254, 3
	s_add_u32 s0, s0, s8
	v_readlane_b32 s2, v254, 18
	s_addc_u32 s1, s1, s9
	s_lshl_b32 s28, s2, 8
	v_readlane_b32 s40, v252, 46
	s_add_u32 s6, s0, s28
	v_readlane_b32 s41, v252, 47
	v_readlane_b32 s42, v252, 48
	v_readlane_b32 s43, v252, 49
	v_readlane_b32 s44, v252, 50
	v_readlane_b32 s45, v252, 51
	v_readlane_b32 s46, v252, 52
	v_readlane_b32 s47, v252, 53
	v_readlane_b32 s48, v252, 54
	v_readlane_b32 s49, v252, 55
	v_readlane_b32 s50, v252, 56
	v_readlane_b32 s51, v252, 57
	s_addc_u32 s7, s1, 0
	s_lshl_b32 s0, s29, 7
	s_lshl_b32 s1, s2, 3
	v_readlane_b32 s52, v252, 58
	v_readlane_b32 s53, v252, 59
	v_readlane_b32 s54, v252, 60
	v_readlane_b32 s55, v252, 61
	s_mov_b64 s[40:41], s[44:45]
	v_mov_b32_e32 v82, v229
	s_add_u32 s10, s40, s1
	s_addc_u32 s11, s41, 0
	v_readfirstlane_b32 s23, v82
	s_ashr_i32 s22, s23, 6
	s_and_b32 s27, s22, 3
	s_lshl_b32 s1, s27, 5
	v_and_b32_e32 v159, 31, v82
	s_or_b32 s24, s1, s0
	s_ashr_i32 s4, s23, 8
	v_or_b32_e32 v182, s24, v159
	v_lshlrev_b32_e32 v0, 12, v182
	s_lshl_b32 s0, s4, 6
	v_bfe_u32 v34, v82, 5, 1
	v_lshl_add_u64 v[2:3], s[6:7], 0, v[0:1]
	s_ashr_i32 s1, s0, 31
	v_lshl_add_u64 v[2:3], s[0:1], 1, v[2:3]
	v_lshlrev_b32_e32 v150, 4, v34
	v_mov_b32_e32 v151, v1
	v_lshl_add_u64 v[2:3], v[2:3], 0, v[150:151]
	flat_load_dwordx4 v[116:119], v[2:3]
	flat_load_dwordx4 v[120:123], v[2:3] offset:32
	flat_load_dwordx4 v[124:127], v[2:3] offset:64
	flat_load_dwordx4 v[128:131], v[2:3] offset:96
	s_movk_i32 s0, 0x280
	v_cmp_gt_i32_e32 vcc, s0, v82
	s_mov_b64 s[42:43], s[46:47]
	s_mov_b64 s[44:45], s[48:49]
	s_mov_b64 s[46:47], s[50:51]
	s_mov_b64 s[48:49], s[52:53]
	s_mov_b64 s[50:51], s[54:55]
	v_readlane_b32 s0, v255, 40
	s_mov_b64 s[12:13], exec
	s_nop 2
	s_cmp_lg_u32 s0, 0
	s_cbranch_scc1 .LBB0_156
	s_and_saveexec_b64 s[12:13], vcc
	s_cbranch_execz .LBB0_156
	v_max_i32_e32 v0, 0x80, v82
	v_sub_u32_e32 v0, v0, v82
	v_add_u32_e32 v0, 0x1ff, v0
	s_movk_i32 s0, 0x1ff
	v_cmp_lt_u32_e32 vcc, s0, v0
	s_mov_b64 s[0:1], -1
	v_mov_b32_e32 v4, v82
	s_and_saveexec_b64 s[14:15], vcc
	s_cbranch_execz .LBB0_149
	v_lshrrev_b32_e32 v0, 9, v0
	v_add_u32_e32 v0, 1, v0
	v_and_b32_e32 v6, 0xfffffe, v0
	v_add_u32_e32 v83, 0x200, v82
	v_readlane_b32 s0, v253, 0
	s_mov_b64 s[18:19], 0
	v_mov_b32_e32 v8, v6
	v_lshl_add_u32 v7, v82, 2, s0
	v_mov_b64_e32 v[2:3], v[82:83]
	s_mov_b32 s2, 0x3fb8aa3b

; template <int MODE>
; DI void attn_unit(LAS unsigned char* lds, const bf16_t* Qg, int ldq, const bf16_t* Kg, int ldk, const bf16_t* VTg, int ldvt, bf16_t* Og, int ldo,
;                   int q0, int NT, const float* gout, const float* relb, float lam, float osc, const float* qgain) {
;     ...
;         c15 = relb[15 * 8 + mm] * LOG2E;
;     }
;     u32x4 kr[KJ], vr[VJ];
.LBB0_156:
	s_or_b64 exec, exec, s[12:13]
	v_readlane_b32 s0, v254, 20
	v_readlane_b32 s1, v254, 21
	s_nop 2
	s_or_b32 s0, s0, s1
	s_cmp_eq_u32 s0, 0
	s_cselect_b32 s0, 1, 0
	v_writelane_b32 v255, s0, 40
	s_ashr_i32 s5, s4, 31
	s_lshl_b64 s[0:1], s[4:5], 2
	s_add_u32 s0, s10, s0
	s_addc_u32 s1, s11, s1
	global_load_dword v18, v1, s[0:1] offset:480
	s_movk_i32 s0, 0x400
	v_ashrrev_i32_e32 v0, 31, v82
	v_cmp_gt_i32_e64 s[38:39], s0, v82
	v_lshrrev_b32_e32 v83, 28, v0
	s_and_saveexec_b64 s[0:1], s[38:39]
	s_cbranch_execz .LBB0_158
	v_add_u32_e32 v0, v82, v83
	v_and_b32_e32 v2, 0x1ffffff0, v0
	v_sub_u32_e32 v4, v82, v2
	v_ashrrev_i32_e32 v2, 4, v0
	v_ashrrev_i32_e32 v3, 31, v2
	v_lshlrev_b64 v[2:3], 12, v[2:3]
	v_lshlrev_b32_e32 v4, 3, v4
	v_lshl_add_u64 v[2:3], s[6:7], 0, v[2:3]
	v_ashrrev_i32_e32 v5, 31, v4
	v_lshl_add_u64 v[2:3], v[4:5], 1, v[2:3]
	flat_load_dwordx4 v[132:135], v[2:3] offset:1024
